# fix: hoisted sgu bias value is read only after its vmcnt wait (rare stale read in the previous two versions); otherwise same as before
# baseline (speedup 1.0000x reference)
.LBB0_266:
	v_add_u32_e32 v226, s31, v125
	v_ashrrev_i32_e32 v227, 31, v226
	v_lshl_add_u64 v[226:227], v[226:227], 2, s[18:19]
	global_load_dword v234, v[226:227], off
	v_add_u32_e32 v228, s31, v124
	v_ashrrev_i32_e32 v229, 31, v228
	v_lshl_add_u64 v[228:229], v[228:229], 2, s[18:19]
	global_load_dword v235, v[228:229], off
	v_add_u32_e32 v230, s31, v51
	v_ashrrev_i32_e32 v231, 31, v230
	v_lshl_add_u64 v[230:231], v[230:231], 2, s[18:19]
	global_load_dword v236, v[230:231], off
	v_add_u32_e32 v232, s31, v50
	v_ashrrev_i32_e32 v233, 31, v232
	v_lshl_add_u64 v[232:233], v[232:233], 2, s[18:19]
	global_load_dword v237, v[232:233], off
	v_cvt_pk_bf16_f32 v20, v24, v25
	ds_write_b16 v102, v20 offset:34816
	ds_write_b16_d16_hi v102, v20 offset:35088
	v_cvt_pk_bf16_f32 v20, v26, v27
	v_cvt_pk_bf16_f32 v16, v16, v17
	ds_write_b16 v102, v20 offset:35360
	ds_write_b16_d16_hi v102, v20 offset:35632
	ds_write_b16 v102, v16 offset:35904
	ds_write_b16_d16_hi v102, v16 offset:36176
	v_cvt_pk_bf16_f32 v16, v18, v19
	ds_write_b16 v102, v16 offset:36448
	ds_write_b16_d16_hi v102, v16 offset:36720
	s_waitcnt lgkmcnt(0)
	s_barrier
	ds_read_b128 v[16:19], v119
	ds_read_b128 v[20:23], v119 offset:4352
	ds_read_b128 v[24:27], v119 offset:8704
	ds_read_b128 v[28:31], v119 offset:13056
	ds_read_b128 v[32:35], v120 offset:34816
	ds_read_b128 v[36:39], v120 offset:35904
	s_waitcnt lgkmcnt(1)
	v_mfma_f32_16x16x32_bf16 v[40:43], v[32:35], v[16:19], 0
	v_add_u32_e32 v56, s31, v125
	v_ashrrev_i32_e32 v57, 31, v56
	v_lshl_add_u64 v[56:57], v[56:57], 2, s[18:19]
	s_waitcnt lgkmcnt(0)
	v_mfma_f32_16x16x32_bf16 v[16:19], v[36:39], v[16:19], 0
	v_or_b32_e32 v48, s31, v63
	v_lshlrev_b32_e32 v144, 1, v48
	v_lshl_add_u64 v[48:49], s[26:27], 0, v[144:145]
	v_mfma_f32_16x16x32_bf16 v[44:47], v[32:35], v[20:23], 0
	s_add_i32 s30, s30, s38
	s_cmpk_lt_i32 s30, 0x440
	v_mfma_f32_16x16x32_bf16 v[20:23], v[36:39], v[20:23], 0
	v_mfma_f32_16x16x32_bf16 v[126:129], v[32:35], v[24:27], 0
	v_mfma_f32_16x16x32_bf16 v[24:27], v[36:39], v[24:27], 0
	v_mfma_f32_16x16x32_bf16 v[32:35], v[32:35], v[28:31], 0
	v_mfma_f32_16x16x32_bf16 v[28:31], v[36:39], v[28:31], 0
	ds_read_b128 v[36:39], v119 offset:64
	ds_read_b128 v[130:133], v119 offset:4416
	ds_read_b128 v[134:137], v119 offset:8768
	ds_read_b128 v[138:141], v119 offset:13120
	ds_read_b128 v[162:165], v121 offset:34816
	ds_read_b128 v[166:169], v121 offset:35904
	s_waitcnt lgkmcnt(1)
	v_mfma_f32_16x16x32_bf16 v[40:43], v[162:165], v[36:39], v[40:43]
	s_waitcnt lgkmcnt(0)
	v_mfma_f32_16x16x32_bf16 v[16:19], v[166:169], v[36:39], v[16:19]
	v_mfma_f32_16x16x32_bf16 v[36:39], v[162:165], v[130:133], v[44:47]
	v_mfma_f32_16x16x32_bf16 v[20:23], v[166:169], v[130:133], v[20:23]
	v_mfma_f32_16x16x32_bf16 v[44:47], v[162:165], v[134:137], v[126:129]
	v_mfma_f32_16x16x32_bf16 v[24:27], v[166:169], v[134:137], v[24:27]
	v_mfma_f32_16x16x32_bf16 v[32:35], v[162:165], v[138:141], v[32:35]
	v_mfma_f32_16x16x32_bf16 v[28:31], v[166:169], v[138:141], v[28:31]
	ds_read_b128 v[126:129], v119 offset:128
	ds_read_b128 v[130:133], v119 offset:4480
	ds_read_b128 v[134:137], v119 offset:8832
	ds_read_b128 v[138:141], v119 offset:13184
	ds_read_b128 v[162:165], v122 offset:34816
	ds_read_b128 v[166:169], v122 offset:35904
	s_waitcnt lgkmcnt(1)
	v_mfma_f32_16x16x32_bf16 v[40:43], v[162:165], v[126:129], v[40:43]
	s_waitcnt lgkmcnt(0)
	v_mfma_f32_16x16x32_bf16 v[16:19], v[166:169], v[126:129], v[16:19]
	v_mfma_f32_16x16x32_bf16 v[36:39], v[162:165], v[130:133], v[36:39]
	v_mfma_f32_16x16x32_bf16 v[20:23], v[166:169], v[130:133], v[20:23]
	v_mfma_f32_16x16x32_bf16 v[126:129], v[162:165], v[134:137], v[44:47]
	v_mfma_f32_16x16x32_bf16 v[24:27], v[166:169], v[134:137], v[24:27]
	v_mfma_f32_16x16x32_bf16 v[130:133], v[162:165], v[138:141], v[32:35]
	v_mfma_f32_16x16x32_bf16 v[134:137], v[166:169], v[138:141], v[28:31]
	s_nop 2
	ds_read_b128 v[28:31], v119 offset:192
	ds_read_b128 v[32:35], v119 offset:4544
	ds_read_b128 v[138:141], v119 offset:8896
	ds_read_b128 v[162:165], v119 offset:13248
	ds_read_b128 v[166:169], v123 offset:34816
	ds_read_b128 v[170:173], v123 offset:35904
	s_waitcnt lgkmcnt(1)
	v_mfma_f32_16x16x32_bf16 v[44:47], v[166:169], v[28:31], v[40:43]
	s_waitcnt lgkmcnt(0)
	v_mfma_f32_16x16x32_bf16 v[40:43], v[170:173], v[28:31], v[16:19]
	s_waitcnt vmcnt(0)
	v_mov_b32_e32 v56, v234
	s_nop 4
	v_pk_add_f32 v[44:45], v[44:45], v[56:57] op_sel_hi:[1,0]
	v_mfma_f32_16x16x32_bf16 v[28:31], v[166:169], v[138:141], v[126:129]
	v_add_f32_e64 v40, v40, v56
	v_add_f32_e64 v41, v41, v56
	v_pk_add_f32 v[42:43], v[42:43], v[56:57] op_sel_hi:[1,0]
	v_pk_add_f32 v[46:47], v[46:47], v[56:57] op_sel_hi:[1,0]
	v_lshlrev_b32_e32 v128, 16, v14
	v_and_b32_e32 v129, 0xffff0000, v14
	v_lshlrev_b32_e32 v14, 16, v15
	v_and_b32_e32 v15, 0xffff0000, v15
	v_lshlrev_b32_e32 v126, 16, v12
	v_and_b32_e32 v127, 0xffff0000, v12
	v_lshlrev_b32_e32 v12, 16, v13
	v_and_b32_e32 v13, 0xffff0000, v13
	v_pk_mul_f32 v[42:43], v[42:43], v[14:15]
	v_pk_mul_f32 v[14:15], v[40:41], v[128:129]
	v_lshlrev_b64 v[40:41], 12, v[54:55]
	v_pk_mul_f32 v[46:47], v[46:47], v[12:13]
	v_pk_mul_f32 v[12:13], v[44:45], v[126:127]
	v_cvt_pk_bf16_f32 v14, v14, v15
	v_lshl_add_u64 v[40:41], v[48:49], 0, v[40:41]
	v_cvt_pk_bf16_f32 v12, v12, v13
	v_cvt_pk_bf16_f32 v13, v46, v47
	v_cvt_pk_bf16_f32 v15, v42, v43
	global_store_dwordx4 v[40:41], v[12:15], off
	v_mfma_f32_16x16x32_bf16 v[36:39], v[166:169], v[32:35], v[36:39]
	v_lshlrev_b32_e32 v42, 16, v10
	v_add_u32_e32 v14, s31, v124
	v_ashrrev_i32_e32 v15, 31, v14
	v_lshl_add_u64 v[14:15], v[14:15], 2, s[18:19]
	v_mov_b32_e32 v14, v235
	v_mfma_f32_16x16x32_bf16 v[32:35], v[170:173], v[32:35], v[20:23]
	v_add_u32_e32 v12, s34, v103
	v_and_b32_e32 v43, 0xffff0000, v10
	v_lshlrev_b32_e32 v10, 16, v11
	v_and_b32_e32 v11, 0xffff0000, v11
	v_ashrrev_i32_e32 v13, 31, v12
	v_lshlrev_b32_e32 v40, 16, v8
	v_and_b32_e32 v41, 0xffff0000, v8
	v_lshlrev_b32_e32 v8, 16, v9
	v_and_b32_e32 v9, 0xffff0000, v9
	v_lshlrev_b64 v[12:13], 12, v[12:13]
	v_lshl_add_u64 v[12:13], v[48:49], 0, v[12:13]
	v_mfma_f32_16x16x32_bf16 v[24:27], v[170:173], v[138:141], v[24:27]
	s_waitcnt vmcnt(0)
	v_pk_add_f32 v[36:37], v[36:37], v[14:15] op_sel_hi:[1,0]
	v_pk_add_f32 v[38:39], v[38:39], v[14:15] op_sel_hi:[1,0]
	v_pk_add_f32 v[32:33], v[32:33], v[14:15] op_sel_hi:[1,0]
	v_pk_add_f32 v[14:15], v[34:35], v[14:15] op_sel_hi:[1,0]
	v_pk_mul_f32 v[38:39], v[38:39], v[8:9]
	v_pk_mul_f32 v[14:15], v[14:15], v[10:11]
	v_pk_mul_f32 v[10:11], v[32:33], v[42:43]
	v_pk_mul_f32 v[8:9], v[36:37], v[40:41]
	v_cvt_pk_bf16_f32 v10, v10, v11
	v_cvt_pk_bf16_f32 v11, v14, v15
	v_lshlrev_b32_e32 v14, 16, v6
	v_cvt_pk_bf16_f32 v8, v8, v9
	v_cvt_pk_bf16_f32 v9, v38, v39
	global_store_dwordx4 v[12:13], v[8:11], off
	v_lshlrev_b32_e32 v12, 16, v4
	v_and_b32_e32 v13, 0xffff0000, v4
	v_add_u32_e32 v10, s31, v51
	v_ashrrev_i32_e32 v11, 31, v10
	v_lshl_add_u64 v[10:11], v[10:11], 2, s[18:19]
	v_mov_b32_e32 v10, v236
	v_add_u32_e32 v8, s34, v104
	v_lshlrev_b32_e32 v4, 16, v5
	v_and_b32_e32 v5, 0xffff0000, v5
	v_and_b32_e32 v15, 0xffff0000, v6
	v_lshlrev_b32_e32 v6, 16, v7
	v_and_b32_e32 v7, 0xffff0000, v7
	v_ashrrev_i32_e32 v9, 31, v8
	v_lshlrev_b64 v[8:9], 12, v[8:9]
	v_lshl_add_u64 v[8:9], v[48:49], 0, v[8:9]
	v_mfma_f32_16x16x32_bf16 v[20:23], v[166:169], v[162:165], v[130:133]
	s_waitcnt vmcnt(0)
	v_pk_add_f32 v[28:29], v[28:29], v[10:11] op_sel_hi:[1,0]
	v_pk_add_f32 v[30:31], v[30:31], v[10:11] op_sel_hi:[1,0]
	v_mfma_f32_16x16x32_bf16 v[16:19], v[170:173], v[162:165], v[134:137]
	v_mul_f32_e64 v30, v30, v4
	v_mul_f32_e64 v31, v31, v5
	v_pk_mul_f32 v[4:5], v[28:29], v[12:13]
	v_pk_add_f32 v[12:13], v[24:25], v[10:11] op_sel_hi:[1,0]
	v_pk_add_f32 v[10:11], v[26:27], v[10:11] op_sel_hi:[1,0]
	v_cvt_pk_bf16_f32 v4, v4, v5
	v_cvt_pk_bf16_f32 v5, v30, v31
	s_nop 0
	v_pk_mul_f32 v[10:11], v[10:11], v[6:7]
	v_pk_mul_f32 v[6:7], v[12:13], v[14:15]
	s_nop 0
	v_cvt_pk_bf16_f32 v6, v6, v7
	v_cvt_pk_bf16_f32 v7, v10, v11
	global_store_dwordx4 v[8:9], v[4:7], off
	v_lshlrev_b32_e32 v8, 16, v0
	v_and_b32_e32 v9, 0xffff0000, v0
	v_add_u32_e32 v6, s31, v50
	v_ashrrev_i32_e32 v7, 31, v6
	v_lshl_add_u64 v[6:7], v[6:7], 2, s[18:19]
	v_mov_b32_e32 v6, v237
	v_add_u32_e32 v4, s34, v105
	v_lshlrev_b32_e32 v0, 16, v1
	v_and_b32_e32 v1, 0xffff0000, v1
	v_ashrrev_i32_e32 v5, 31, v4
	v_lshlrev_b32_e32 v10, 16, v2
	v_and_b32_e32 v11, 0xffff0000, v2
	v_lshlrev_b32_e32 v2, 16, v3
	v_and_b32_e32 v3, 0xffff0000, v3
	v_lshlrev_b64 v[4:5], 12, v[4:5]
	v_lshl_add_u64 v[4:5], v[48:49], 0, v[4:5]
	s_waitcnt vmcnt(0)
	v_pk_add_f32 v[12:13], v[20:21], v[6:7] op_sel_hi:[1,0]
	v_pk_add_f32 v[14:15], v[22:23], v[6:7] op_sel_hi:[1,0]
	s_nop 0
	v_pk_mul_f32 v[14:15], v[14:15], v[0:1]
	v_pk_mul_f32 v[0:1], v[12:13], v[8:9]
	v_pk_add_f32 v[8:9], v[16:17], v[6:7] op_sel_hi:[1,0]
	v_pk_add_f32 v[6:7], v[18:19], v[6:7] op_sel_hi:[1,0]
	v_cvt_pk_bf16_f32 v0, v0, v1
	v_cvt_pk_bf16_f32 v1, v14, v15
	s_nop 0
	v_pk_mul_f32 v[6:7], v[6:7], v[2:3]
	v_pk_mul_f32 v[2:3], v[8:9], v[10:11]
	s_nop 0
	v_cvt_pk_bf16_f32 v2, v2, v3
	v_cvt_pk_bf16_f32 v3, v6, v7
	global_store_dwordx4 v[4:5], v[0:3], off
	s_cbranch_scc0 .LBB0_277
